# v039staticprio
# baseline (speedup 1.0000x reference)
; DEV char* opaque_ptr(char* q) { asm volatile("" : "+s"(q)); return q; }
; __device__ void phase0(const P& p) {
;   char* ws = opaque_ptr(p.ws);
;   const size_t gtid = (size_t)blockIdx.x * 512 + threadIdx.x;
;   const size_t gsz = (size_t)gridDim.x * 512;
;   HALF* x16 = (HALF*)(ws + OFF_X16);
;   const size_t nvec = (size_t)NTOK * 1024 / 8;
;   const size_t npv = (size_t)NPROMPT * 1024 / 8;
;   for (size_t i = gtid; i < nvec; i += gsz) {
;     const float* src = (i < npv) ? (p.xp + i * 8) : (p.xs + (i - npv) * 8);
; __global__ void __launch_bounds__(512, 2) mega(P p) {
;   cg::grid_group grid = cg::this_grid();
;   extern __shared__ __attribute__((aligned(16))) HALF sm[];
;   char* ws = opaque_ptr(p.ws);
;   const int nb = gridDim.x;
;   const int hf = __builtin_amdgcn_readfirstlane((int)(threadIdx.x >> 8));
;   HALF* smh = sm + hf * 36864;
;   phase0(p);
_Z4mega1P:
	s_load_dwordx16 s[48:63], s[0:1], 0x0
	s_load_dwordx8 s[24:31], s[0:1], 0x60
	s_load_dwordx8 s[4:11], s[0:1], 0x40
	s_add_u32 s44, s0, 0x78
	s_addc_u32 s45, s1, 0
	s_load_dword s34, s[0:1], 0x80
	s_waitcnt lgkmcnt(0)
	s_mov_b64 s[0:1], s[28:29]
	v_writelane_b32 v254, s4, 0
	s_mov_b32 s3, 0
	v_and_b32_e32 v155, 0x3ff, v0
	v_writelane_b32 v254, s5, 1
	v_writelane_b32 v254, s6, 2
	v_writelane_b32 v254, s7, 3
	v_writelane_b32 v254, s8, 4
	v_writelane_b32 v254, s9, 5
	v_writelane_b32 v254, s10, 6
	v_writelane_b32 v254, s11, 7
	v_writelane_b32 v254, s0, 8
	s_mov_b32 s38, s30
	v_readfirstlane_b32 s33, v155
	s_nop 3
	s_cmp_ge_u32 s33, 0x100
	s_cbranch_scc0 .Lprio_done
	s_setprio 1
.Lprio_done:
	v_writelane_b32 v254, s1, 9
	s_lshl_b64 s[0:1], s[2:3], 9
	v_or_b32_e32 v2, s0, v155
	v_mov_b32_e32 v3, s1
	v_writelane_b32 v254, s2, 10
	s_mov_b32 s39, s3
	s_mov_b64 s[0:1], 0xa00000
	s_mov_b64 s[36:37], s[28:29]
	v_mov_b32_e32 v7, 0
	v_writelane_b32 v254, s3, 11
	s_lshl_b64 s[6:7], s[38:39], 9
	v_cmp_gt_u64_e32 vcc, s[0:1], v[2:3]
	s_and_saveexec_b64 s[0:1], vcc
	s_cbranch_execz .LBB0_3
	v_readlane_b32 s2, v254, 10
	v_readlane_b32 s3, v254, 11
	s_lshl_b64 s[4:5], s[2:3], 13
	s_add_u32 s4, s36, s4
	v_lshlrev_b32_e32 v6, 4, v155
	s_addc_u32 s5, s37, s5
	v_lshl_add_u64 v[4:5], s[4:5], 0, v[6:7]
	s_mov_b64 s[4:5], 0x3eb0000
	v_lshl_add_u64 v[4:5], v[4:5], 0, s[4:5]
	s_lshl_b64 s[4:5], s[38:39], 13
	s_add_u32 s8, s50, 0xfc000000
	s_addc_u32 s9, s51, -1
	s_lshl_b64 s[10:11], s[2:3], 14
	v_lshlrev_b32_e32 v6, 5, v155
	v_lshl_add_u64 v[6:7], s[10:11], 0, v[6:7]
	s_lshl_b64 s[10:11], s[38:39], 14
	s_mov_b64 s[12:13], 0
	s_mov_b64 s[14:15], 0x200000
	s_mov_b64 s[16:17], 0x9fffff
	v_mov_b64_e32 v[8:9], v[2:3]
	s_cmp_eq_u32 s38, 0x100
	s_cbranch_scc0 .LBB0_2
	s_mov_b64 s[18:19], s[48:49]
	s_mov_b32 s20, 0
	s_mov_b64 s[22:23], 0x1000000
